# kv up-projection epilogue rewritten (one LDS read of the 32 row scales, running row address, paired bf16 stores: 393 instead of 2700 instructions) and the gated-merge step-1 epilogue software-pipeline
# speedup vs baseline: 1.0075x; 1.0075x over previous
; DEV unsigned cvtpk(float lo, float hi) { f32x2 v = {lo, hi}; bf16x2_t b = __builtin_convertvector(v, bf16x2_t); return __builtin_bit_cast(unsigned, b); }
; DEV float bflo(unsigned w) { return __uint_as_float(w << 16); }
; DEV float bfhi(unsigned w) { return __uint_as_float(w & 0xffff0000u); }
;   __device__ __forceinline__ void operator()(const pg8::f32x4 (&acc)[2][2][4][2], const pg8::Unit& u, int wr, int wc, int fr, int fq) const {
; #pragma unroll
;     for (int ai = 0; ai < 2; ++ai)
; #pragma unroll
;       for (int m = 0; m < 4; ++m) {
;         const int row = u.pm * 256 + ai * 128 + wr * 64 + m * 16 + fr; const int c0 = u.pn * 256 + wc * 32 + 4 * fq;
; #pragma unroll
;         for (int bj = 0; bj < 2; ++bj)
; #pragma unroll
;           for (int n = 0; n < 2; ++n) {
;             const int c = c0 + bj * 128 + n * 16;
;             const u32x2 gw = *(const u32x2*)(G + (size_t)row * INP + c);
;             pg8::f32x4 v = acc[ai][bj][m][n];
;             v[0] *= bflo(gw[0]); v[1] *= bfhi(gw[0]); v[2] *= bflo(gw[1]); v[3] *= bfhi(gw[1]);
;             float* mp = MACC + (size_t)row * 1024 + c;
;             if (STEP > 0) v += *(const pg8::f32x4*)mp;
;             if (STEP < 2) *(pg8::f32x4*)mp = v;
;             else { u32x2 w; w[0] = cvtpk(v[0], v[1]); w[1] = cvtpk(v[2], v[3]); *(u32x2*)(OUT + (size_t)row * 1024 + c) = w; }
;           }
;       }
;   }
.LBB0_276:
	v_readlane_b32 s0, v250, 17
	v_lshl_add_u32 v136, s87, 8, v144
	v_lshl_or_b32 v138, s86, 8, v146
	v_readlane_b32 s1, v250, 18
	v_ashrrev_i32_e32 v137, 31, v136
	v_ashrrev_i32_e32 v139, 31, v138
	v_mov_b64_e32 v[140:141], s[0:1]
	v_lshlrev_b64 v[148:149], 12, v[136:137]
	v_mad_i64_i32 v[150:151], s[42:43], v136, s89, v[140:141]
	v_lshlrev_b64 v[142:143], 1, v[138:139]
	v_lshl_add_u64 v[152:153], v[150:151], 0, v[142:143]
	v_lshl_add_u64 v[148:149], s[78:79], 0, v[148:149]
	v_lshlrev_b64 v[138:139], 2, v[138:139]
	v_lshl_add_u64 v[156:157], v[148:149], 0, v[138:139]
	s_andn2_b64 vcc, exec, s[40:41]
	s_mov_b64 s[40:41], -1
	global_load_dwordx2 v[136:137], v[152:153], off offset:0
	global_load_dwordx2 v[138:139], v[152:153], off offset:32
	global_load_dwordx2 v[140:141], v[152:153], off offset:256
	global_load_dwordx2 v[142:143], v[152:153], off offset:288
	v_mov_b64_e32 v[214:215], v[156:157]
	global_load_dwordx4 v[160:163], v[156:157], off offset:0
	global_load_dwordx4 v[164:167], v[156:157], off offset:64
	global_load_dwordx4 v[168:171], v[156:157], off offset:512
	global_load_dwordx4 v[172:175], v[156:157], off offset:576
	s_mov_b64 s[0:1], 0x3a000
	v_lshl_add_u64 v[152:153], v[152:153], 0, s[0:1]
	s_mov_b64 s[0:1], 0x10000
	v_lshl_add_u64 v[156:157], v[156:157], 0, s[0:1]
	global_load_dwordx2 v[148:149], v[152:153], off offset:0
	global_load_dwordx2 v[150:151], v[152:153], off offset:32
	global_load_dwordx2 v[198:199], v[152:153], off offset:256
	global_load_dwordx2 v[200:201], v[152:153], off offset:288
	v_mov_b64_e32 v[216:217], v[156:157]
	global_load_dwordx4 v[176:179], v[156:157], off offset:0
	global_load_dwordx4 v[180:183], v[156:157], off offset:64
	global_load_dwordx4 v[184:187], v[156:157], off offset:512
	global_load_dwordx4 v[188:191], v[156:157], off offset:576
	s_mov_b64 s[0:1], 0x3a000
	v_lshl_add_u64 v[152:153], v[152:153], 0, s[0:1]
	s_mov_b64 s[0:1], 0x10000
	v_lshl_add_u64 v[156:157], v[156:157], 0, s[0:1]
	s_waitcnt vmcnt(11)
	v_lshlrev_b32_e32 v218, 16, v136
	v_and_b32_e32 v219, 0xffff0000, v136
	v_lshlrev_b32_e32 v220, 16, v137
	v_and_b32_e32 v221, 0xffff0000, v137
	v_fma_f32 v160, v124, v218, v160
	v_fma_f32 v161, v125, v219, v161
	v_fma_f32 v162, v126, v220, v162
	v_fma_f32 v163, v127, v221, v163
	global_store_dwordx4 v[214:215], v[160:163], off offset:0
	s_waitcnt vmcnt(11)
	v_lshlrev_b32_e32 v218, 16, v138
	v_and_b32_e32 v219, 0xffff0000, v138
	v_lshlrev_b32_e32 v220, 16, v139
	v_and_b32_e32 v221, 0xffff0000, v139
	v_fma_f32 v164, v120, v218, v164
	v_fma_f32 v165, v121, v219, v165
	v_fma_f32 v166, v122, v220, v166
	v_fma_f32 v167, v123, v221, v167
	global_store_dwordx4 v[214:215], v[164:167], off offset:64
	s_waitcnt vmcnt(11)
	v_lshlrev_b32_e32 v218, 16, v140
	v_and_b32_e32 v219, 0xffff0000, v140
	v_lshlrev_b32_e32 v220, 16, v141
	v_and_b32_e32 v221, 0xffff0000, v141
	v_fma_f32 v168, v116, v218, v168
	v_fma_f32 v169, v117, v219, v169
	v_fma_f32 v170, v118, v220, v170
	v_fma_f32 v171, v119, v221, v171
	global_store_dwordx4 v[214:215], v[168:171], off offset:512
	s_waitcnt vmcnt(11)
	v_lshlrev_b32_e32 v218, 16, v142
	v_and_b32_e32 v219, 0xffff0000, v142
	v_lshlrev_b32_e32 v220, 16, v143
	v_and_b32_e32 v221, 0xffff0000, v143
	v_fma_f32 v172, v108, v218, v172
	v_fma_f32 v173, v109, v219, v173
	v_fma_f32 v174, v110, v220, v174
	v_fma_f32 v175, v111, v221, v175
	global_store_dwordx4 v[214:215], v[172:175], off offset:576
	global_load_dwordx2 v[136:137], v[152:153], off offset:0
	global_load_dwordx2 v[138:139], v[152:153], off offset:32
	global_load_dwordx2 v[140:141], v[152:153], off offset:256
	global_load_dwordx2 v[142:143], v[152:153], off offset:288
	v_mov_b64_e32 v[214:215], v[156:157]
	global_load_dwordx4 v[160:163], v[156:157], off offset:0
	global_load_dwordx4 v[164:167], v[156:157], off offset:64
	global_load_dwordx4 v[168:171], v[156:157], off offset:512
	global_load_dwordx4 v[172:175], v[156:157], off offset:576
	s_mov_b64 s[0:1], 0x3a000
	v_lshl_add_u64 v[152:153], v[152:153], 0, s[0:1]
	s_mov_b64 s[0:1], 0x10000
	v_lshl_add_u64 v[156:157], v[156:157], 0, s[0:1]
	s_waitcnt vmcnt(15)
	v_lshlrev_b32_e32 v218, 16, v148
	v_and_b32_e32 v219, 0xffff0000, v148
	v_lshlrev_b32_e32 v220, 16, v149
	v_and_b32_e32 v221, 0xffff0000, v149
	v_fma_f32 v176, v112, v218, v176
	v_fma_f32 v177, v113, v219, v177
	v_fma_f32 v178, v114, v220, v178
	v_fma_f32 v179, v115, v221, v179
	global_store_dwordx4 v[216:217], v[176:179], off offset:0
	s_waitcnt vmcnt(15)
	v_lshlrev_b32_e32 v218, 16, v150
	v_and_b32_e32 v219, 0xffff0000, v150
	v_lshlrev_b32_e32 v220, 16, v151
	v_and_b32_e32 v221, 0xffff0000, v151
	v_fma_f32 v180, v104, v218, v180
	v_fma_f32 v181, v105, v219, v181
	v_fma_f32 v182, v106, v220, v182
	v_fma_f32 v183, v107, v221, v183
	global_store_dwordx4 v[216:217], v[180:183], off offset:64
	s_waitcnt vmcnt(15)
	v_lshlrev_b32_e32 v218, 16, v198
	v_and_b32_e32 v219, 0xffff0000, v198
	v_lshlrev_b32_e32 v220, 16, v199
	v_and_b32_e32 v221, 0xffff0000, v199
	v_fma_f32 v184, v100, v218, v184
	v_fma_f32 v185, v101, v219, v185
	v_fma_f32 v186, v102, v220, v186
	v_fma_f32 v187, v103, v221, v187
	global_store_dwordx4 v[216:217], v[184:187], off offset:512
	s_waitcnt vmcnt(15)
; DEV unsigned cvtpk(float lo, float hi) { f32x2 v = {lo, hi}; bf16x2_t b = __builtin_convertvector(v, bf16x2_t); return __builtin_bit_cast(unsigned, b); }
; DEV float bflo(unsigned w) { return __uint_as_float(w << 16); }
; DEV float bfhi(unsigned w) { return __uint_as_float(w & 0xffff0000u); }
;   __device__ __forceinline__ void operator()(const pg8::f32x4 (&acc)[2][2][4][2], const pg8::Unit& u, int wr, int wc, int fr, int fq) const {
; #pragma unroll
;     for (int ai = 0; ai < 2; ++ai)
; #pragma unroll
;       for (int m = 0; m < 4; ++m) {
;         const int row = u.pm * 256 + ai * 128 + wr * 64 + m * 16 + fr; const int c0 = u.pn * 256 + wc * 32 + 4 * fq;
; #pragma unroll
;         for (int bj = 0; bj < 2; ++bj)
; #pragma unroll
;           for (int n = 0; n < 2; ++n) {
;             const int c = c0 + bj * 128 + n * 16;
;             const u32x2 gw = *(const u32x2*)(G + (size_t)row * INP + c);
;             pg8::f32x4 v = acc[ai][bj][m][n];
;             v[0] *= bflo(gw[0]); v[1] *= bfhi(gw[0]); v[2] *= bflo(gw[1]); v[3] *= bfhi(gw[1]);
;             float* mp = MACC + (size_t)row * 1024 + c;
;             if (STEP > 0) v += *(const pg8::f32x4*)mp;
;             if (STEP < 2) *(pg8::f32x4*)mp = v;
;             else { u32x2 w; w[0] = cvtpk(v[0], v[1]); w[1] = cvtpk(v[2], v[3]); *(u32x2*)(OUT + (size_t)row * 1024 + c) = w; }
;           }
;       }
;   }
	v_lshlrev_b32_e32 v218, 16, v200
	v_and_b32_e32 v219, 0xffff0000, v200
	v_lshlrev_b32_e32 v220, 16, v201
	v_and_b32_e32 v221, 0xffff0000, v201
	v_fma_f32 v188, v92, v218, v188
	v_fma_f32 v189, v93, v219, v189
	v_fma_f32 v190, v94, v220, v190
	v_fma_f32 v191, v95, v221, v191
	global_store_dwordx4 v[216:217], v[188:191], off offset:576
	global_load_dwordx2 v[148:149], v[152:153], off offset:0
	global_load_dwordx2 v[150:151], v[152:153], off offset:32
	global_load_dwordx2 v[198:199], v[152:153], off offset:256
	global_load_dwordx2 v[200:201], v[152:153], off offset:288
	v_mov_b64_e32 v[216:217], v[156:157]
	global_load_dwordx4 v[176:179], v[156:157], off offset:0
	global_load_dwordx4 v[180:183], v[156:157], off offset:64
	global_load_dwordx4 v[184:187], v[156:157], off offset:512
	global_load_dwordx4 v[188:191], v[156:157], off offset:576
	s_mov_b64 s[0:1], 0x122000
	v_lshl_add_u64 v[152:153], v[152:153], 0, s[0:1]
	s_mov_b64 s[0:1], 0x50000
	v_lshl_add_u64 v[156:157], v[156:157], 0, s[0:1]
	s_waitcnt vmcnt(15)
	v_lshlrev_b32_e32 v218, 16, v136
	v_and_b32_e32 v219, 0xffff0000, v136
	v_lshlrev_b32_e32 v220, 16, v137
	v_and_b32_e32 v221, 0xffff0000, v137
	v_fma_f32 v160, v96, v218, v160
	v_fma_f32 v161, v97, v219, v161
	v_fma_f32 v162, v98, v220, v162
	v_fma_f32 v163, v99, v221, v163
	global_store_dwordx4 v[214:215], v[160:163], off offset:0
	s_waitcnt vmcnt(15)
	v_lshlrev_b32_e32 v218, 16, v138
	v_and_b32_e32 v219, 0xffff0000, v138
	v_lshlrev_b32_e32 v220, 16, v139
	v_and_b32_e32 v221, 0xffff0000, v139
	v_fma_f32 v164, v88, v218, v164
	v_fma_f32 v165, v89, v219, v165
	v_fma_f32 v166, v90, v220, v166
	v_fma_f32 v167, v91, v221, v167
	global_store_dwordx4 v[214:215], v[164:167], off offset:64
	s_waitcnt vmcnt(15)
	v_lshlrev_b32_e32 v218, 16, v140
	v_and_b32_e32 v219, 0xffff0000, v140
	v_lshlrev_b32_e32 v220, 16, v141
	v_and_b32_e32 v221, 0xffff0000, v141
	v_fma_f32 v168, v84, v218, v168
	v_fma_f32 v169, v85, v219, v169
	v_fma_f32 v170, v86, v220, v170
	v_fma_f32 v171, v87, v221, v171
	global_store_dwordx4 v[214:215], v[168:171], off offset:512
	s_waitcnt vmcnt(15)
	v_lshlrev_b32_e32 v218, 16, v142
	v_and_b32_e32 v219, 0xffff0000, v142
	v_lshlrev_b32_e32 v220, 16, v143
	v_and_b32_e32 v221, 0xffff0000, v143
	v_fma_f32 v172, v76, v218, v172
	v_fma_f32 v173, v77, v219, v173
	v_fma_f32 v174, v78, v220, v174
	v_fma_f32 v175, v79, v221, v175
	global_store_dwordx4 v[214:215], v[172:175], off offset:576
	global_load_dwordx2 v[136:137], v[152:153], off offset:0
	global_load_dwordx2 v[138:139], v[152:153], off offset:32
	global_load_dwordx2 v[140:141], v[152:153], off offset:256
	global_load_dwordx2 v[142:143], v[152:153], off offset:288
	v_mov_b64_e32 v[214:215], v[156:157]
	global_load_dwordx4 v[160:163], v[156:157], off offset:0
	global_load_dwordx4 v[164:167], v[156:157], off offset:64
	global_load_dwordx4 v[168:171], v[156:157], off offset:512
	global_load_dwordx4 v[172:175], v[156:157], off offset:576
	s_mov_b64 s[0:1], 0x3a000
	v_lshl_add_u64 v[152:153], v[152:153], 0, s[0:1]
	s_mov_b64 s[0:1], 0x10000
	v_lshl_add_u64 v[156:157], v[156:157], 0, s[0:1]
	s_waitcnt vmcnt(15)
	v_lshlrev_b32_e32 v218, 16, v148
	v_and_b32_e32 v219, 0xffff0000, v148
	v_lshlrev_b32_e32 v220, 16, v149
	v_and_b32_e32 v221, 0xffff0000, v149
	v_fma_f32 v176, v80, v218, v176
	v_fma_f32 v177, v81, v219, v177
	v_fma_f32 v178, v82, v220, v178
	v_fma_f32 v179, v83, v221, v179
	global_store_dwordx4 v[216:217], v[176:179], off offset:0
	s_waitcnt vmcnt(15)
	v_lshlrev_b32_e32 v218, 16, v150
	v_and_b32_e32 v219, 0xffff0000, v150
	v_lshlrev_b32_e32 v220, 16, v151
	v_and_b32_e32 v221, 0xffff0000, v151
	v_fma_f32 v180, v72, v218, v180
	v_fma_f32 v181, v73, v219, v181
	v_fma_f32 v182, v74, v220, v182
	v_fma_f32 v183, v75, v221, v183
	global_store_dwordx4 v[216:217], v[180:183], off offset:64
	s_waitcnt vmcnt(15)
	v_lshlrev_b32_e32 v218, 16, v198
	v_and_b32_e32 v219, 0xffff0000, v198
	v_lshlrev_b32_e32 v220, 16, v199
	v_and_b32_e32 v221, 0xffff0000, v199
	v_fma_f32 v184, v68, v218, v184
	v_fma_f32 v185, v69, v219, v185
	v_fma_f32 v186, v70, v220, v186
	v_fma_f32 v187, v71, v221, v187
	global_store_dwordx4 v[216:217], v[184:187], off offset:512
	s_waitcnt vmcnt(15)
	v_lshlrev_b32_e32 v218, 16, v200
	v_and_b32_e32 v219, 0xffff0000, v200
	v_lshlrev_b32_e32 v220, 16, v201
	v_and_b32_e32 v221, 0xffff0000, v201
	v_fma_f32 v188, v64, v218, v188
	v_fma_f32 v189, v65, v219, v189
	v_fma_f32 v190, v66, v220, v190
	v_fma_f32 v191, v67, v221, v191
	global_store_dwordx4 v[216:217], v[188:191], off offset:576
	global_load_dwordx2 v[148:149], v[152:153], off offset:0
	global_load_dwordx2 v[150:151], v[152:153], off offset:32
	global_load_dwordx2 v[198:199], v[152:153], off offset:256
	global_load_dwordx2 v[200:201], v[152:153], off offset:288
	v_mov_b64_e32 v[216:217], v[156:157]
	global_load_dwordx4 v[176:179], v[156:157], off offset:0
	global_load_dwordx4 v[180:183], v[156:157], off offset:64
	global_load_dwordx4 v[184:187], v[156:157], off offset:512
	global_load_dwordx4 v[188:191], v[156:157], off offset:576
	s_mov_b64 s[0:1], 0x3a000
	v_lshl_add_u64 v[152:153], v[152:153], 0, s[0:1]
	s_mov_b64 s[0:1], 0x10000
	v_lshl_add_u64 v[156:157], v[156:157], 0, s[0:1]
	s_waitcnt vmcnt(15)
	v_lshlrev_b32_e32 v218, 16, v136
	v_and_b32_e32 v219, 0xffff0000, v136
	v_lshlrev_b32_e32 v220, 16, v137
	v_and_b32_e32 v221, 0xffff0000, v137
	v_fma_f32 v160, v60, v218, v160
	v_fma_f32 v161, v61, v219, v161
	v_fma_f32 v162, v62, v220, v162
	v_fma_f32 v163, v63, v221, v163
	global_store_dwordx4 v[214:215], v[160:163], off offset:0
	s_waitcnt vmcnt(15)
; DEV unsigned cvtpk(float lo, float hi) { f32x2 v = {lo, hi}; bf16x2_t b = __builtin_convertvector(v, bf16x2_t); return __builtin_bit_cast(unsigned, b); }
; DEV float bflo(unsigned w) { return __uint_as_float(w << 16); }
; DEV float bfhi(unsigned w) { return __uint_as_float(w & 0xffff0000u); }
;   __device__ __forceinline__ void operator()(const pg8::f32x4 (&acc)[2][2][4][2], const pg8::Unit& u, int wr, int wc, int fr, int fq) const {
; #pragma unroll
;     for (int ai = 0; ai < 2; ++ai)
; #pragma unroll
;       for (int m = 0; m < 4; ++m) {
;         const int row = u.pm * 256 + ai * 128 + wr * 64 + m * 16 + fr; const int c0 = u.pn * 256 + wc * 32 + 4 * fq;
; #pragma unroll
;         for (int bj = 0; bj < 2; ++bj)
; #pragma unroll
;           for (int n = 0; n < 2; ++n) {
;             const int c = c0 + bj * 128 + n * 16;
;             const u32x2 gw = *(const u32x2*)(G + (size_t)row * INP + c);
;             pg8::f32x4 v = acc[ai][bj][m][n];
;             v[0] *= bflo(gw[0]); v[1] *= bfhi(gw[0]); v[2] *= bflo(gw[1]); v[3] *= bfhi(gw[1]);
;             float* mp = MACC + (size_t)row * 1024 + c;
;             if (STEP > 0) v += *(const pg8::f32x4*)mp;
;             if (STEP < 2) *(pg8::f32x4*)mp = v;
;             else { u32x2 w; w[0] = cvtpk(v[0], v[1]); w[1] = cvtpk(v[2], v[3]); *(u32x2*)(OUT + (size_t)row * 1024 + c) = w; }
;           }
;       }
;   }
	v_lshlrev_b32_e32 v218, 16, v138
	v_and_b32_e32 v219, 0xffff0000, v138
	v_lshlrev_b32_e32 v220, 16, v139
	v_and_b32_e32 v221, 0xffff0000, v139
	v_fma_f32 v164, v56, v218, v164
	v_fma_f32 v165, v57, v219, v165
	v_fma_f32 v166, v58, v220, v166
	v_fma_f32 v167, v59, v221, v167
	global_store_dwordx4 v[214:215], v[164:167], off offset:64
	s_waitcnt vmcnt(15)
	v_lshlrev_b32_e32 v218, 16, v140
	v_and_b32_e32 v219, 0xffff0000, v140
	v_lshlrev_b32_e32 v220, 16, v141
	v_and_b32_e32 v221, 0xffff0000, v141
	v_fma_f32 v168, v52, v218, v168
	v_fma_f32 v169, v53, v219, v169
	v_fma_f32 v170, v54, v220, v170
	v_fma_f32 v171, v55, v221, v171
	global_store_dwordx4 v[214:215], v[168:171], off offset:512
	s_waitcnt vmcnt(15)
	v_lshlrev_b32_e32 v218, 16, v142
	v_and_b32_e32 v219, 0xffff0000, v142
	v_lshlrev_b32_e32 v220, 16, v143
	v_and_b32_e32 v221, 0xffff0000, v143
	v_fma_f32 v172, v44, v218, v172
	v_fma_f32 v173, v45, v219, v173
	v_fma_f32 v174, v46, v220, v174
	v_fma_f32 v175, v47, v221, v175
	global_store_dwordx4 v[214:215], v[172:175], off offset:576
	global_load_dwordx2 v[136:137], v[152:153], off offset:0
	global_load_dwordx2 v[138:139], v[152:153], off offset:32
	global_load_dwordx2 v[140:141], v[152:153], off offset:256
	global_load_dwordx2 v[142:143], v[152:153], off offset:288
	v_mov_b64_e32 v[214:215], v[156:157]
	global_load_dwordx4 v[160:163], v[156:157], off offset:0
	global_load_dwordx4 v[164:167], v[156:157], off offset:64
	global_load_dwordx4 v[168:171], v[156:157], off offset:512
	global_load_dwordx4 v[172:175], v[156:157], off offset:576
	s_mov_b64 s[0:1], 0x3a000
	v_lshl_add_u64 v[152:153], v[152:153], 0, s[0:1]
	s_mov_b64 s[0:1], 0x10000
	v_lshl_add_u64 v[156:157], v[156:157], 0, s[0:1]
	s_waitcnt vmcnt(15)
	v_lshlrev_b32_e32 v218, 16, v148
	v_and_b32_e32 v219, 0xffff0000, v148
	v_lshlrev_b32_e32 v220, 16, v149
	v_and_b32_e32 v221, 0xffff0000, v149
	v_fma_f32 v176, v48, v218, v176
	v_fma_f32 v177, v49, v219, v177
	v_fma_f32 v178, v50, v220, v178
	v_fma_f32 v179, v51, v221, v179
	global_store_dwordx4 v[216:217], v[176:179], off offset:0
	s_waitcnt vmcnt(15)
	v_lshlrev_b32_e32 v218, 16, v150
	v_and_b32_e32 v219, 0xffff0000, v150
	v_lshlrev_b32_e32 v220, 16, v151
	v_and_b32_e32 v221, 0xffff0000, v151
	v_fma_f32 v180, v40, v218, v180
	v_fma_f32 v181, v41, v219, v181
	v_fma_f32 v182, v42, v220, v182
	v_fma_f32 v183, v43, v221, v183
	global_store_dwordx4 v[216:217], v[180:183], off offset:64
	s_waitcnt vmcnt(15)
	v_lshlrev_b32_e32 v218, 16, v198
	v_and_b32_e32 v219, 0xffff0000, v198
	v_lshlrev_b32_e32 v220, 16, v199
	v_and_b32_e32 v221, 0xffff0000, v199
	v_fma_f32 v184, v36, v218, v184
	v_fma_f32 v185, v37, v219, v185
	v_fma_f32 v186, v38, v220, v186
	v_fma_f32 v187, v39, v221, v187
	global_store_dwordx4 v[216:217], v[184:187], off offset:512
	s_waitcnt vmcnt(15)
	v_lshlrev_b32_e32 v218, 16, v200
	v_and_b32_e32 v219, 0xffff0000, v200
	v_lshlrev_b32_e32 v220, 16, v201
	v_and_b32_e32 v221, 0xffff0000, v201
	v_fma_f32 v188, v28, v218, v188
	v_fma_f32 v189, v29, v219, v189
	v_fma_f32 v190, v30, v220, v190
	v_fma_f32 v191, v31, v221, v191
	global_store_dwordx4 v[216:217], v[188:191], off offset:576
	global_load_dwordx2 v[148:149], v[152:153], off offset:0
	global_load_dwordx2 v[150:151], v[152:153], off offset:32
	global_load_dwordx2 v[198:199], v[152:153], off offset:256
	global_load_dwordx2 v[200:201], v[152:153], off offset:288
	v_mov_b64_e32 v[216:217], v[156:157]
	global_load_dwordx4 v[176:179], v[156:157], off offset:0
	global_load_dwordx4 v[180:183], v[156:157], off offset:64
	global_load_dwordx4 v[184:187], v[156:157], off offset:512
	global_load_dwordx4 v[188:191], v[156:157], off offset:576
	s_waitcnt vmcnt(15)
	v_lshlrev_b32_e32 v218, 16, v136
	v_and_b32_e32 v219, 0xffff0000, v136
	v_lshlrev_b32_e32 v220, 16, v137
	v_and_b32_e32 v221, 0xffff0000, v137
	v_fma_f32 v160, v32, v218, v160
	v_fma_f32 v161, v33, v219, v161
	v_fma_f32 v162, v34, v220, v162
	v_fma_f32 v163, v35, v221, v163
	global_store_dwordx4 v[214:215], v[160:163], off offset:0
	s_waitcnt vmcnt(15)
	v_lshlrev_b32_e32 v218, 16, v138
	v_and_b32_e32 v219, 0xffff0000, v138
	v_lshlrev_b32_e32 v220, 16, v139
	v_and_b32_e32 v221, 0xffff0000, v139
	v_fma_f32 v164, v24, v218, v164
	v_fma_f32 v165, v25, v219, v165
	v_fma_f32 v166, v26, v220, v166
	v_fma_f32 v167, v27, v221, v167
	global_store_dwordx4 v[214:215], v[164:167], off offset:64
	s_waitcnt vmcnt(15)
	v_lshlrev_b32_e32 v218, 16, v140
	v_and_b32_e32 v219, 0xffff0000, v140
	v_lshlrev_b32_e32 v220, 16, v141
	v_and_b32_e32 v221, 0xffff0000, v141
	v_fma_f32 v168, v20, v218, v168
	v_fma_f32 v169, v21, v219, v169
	v_fma_f32 v170, v22, v220, v170
	v_fma_f32 v171, v23, v221, v171
	global_store_dwordx4 v[214:215], v[168:171], off offset:512
	s_waitcnt vmcnt(15)
	v_lshlrev_b32_e32 v218, 16, v142
	v_and_b32_e32 v219, 0xffff0000, v142
	v_lshlrev_b32_e32 v220, 16, v143
	v_and_b32_e32 v221, 0xffff0000, v143
	v_fma_f32 v172, v12, v218, v172
	v_fma_f32 v173, v13, v219, v173
	v_fma_f32 v174, v14, v220, v174
	v_fma_f32 v175, v15, v221, v175
	global_store_dwordx4 v[214:215], v[172:175], off offset:576
	s_waitcnt vmcnt(7)
	v_lshlrev_b32_e32 v218, 16, v148
	v_and_b32_e32 v219, 0xffff0000, v148
	v_lshlrev_b32_e32 v220, 16, v149
	v_and_b32_e32 v221, 0xffff0000, v149
	v_fma_f32 v176, v16, v218, v176
	v_fma_f32 v177, v17, v219, v177
	v_fma_f32 v178, v18, v220, v178
	v_fma_f32 v179, v19, v221, v179
	global_store_dwordx4 v[216:217], v[176:179], off offset:0
	s_waitcnt vmcnt(7)
	v_lshlrev_b32_e32 v218, 16, v150
	v_and_b32_e32 v219, 0xffff0000, v150
	v_lshlrev_b32_e32 v220, 16, v151
	v_and_b32_e32 v221, 0xffff0000, v151
	v_fma_f32 v180, v8, v218, v180
	v_fma_f32 v181, v9, v219, v181
	v_fma_f32 v182, v10, v220, v182
	v_fma_f32 v183, v11, v221, v183
	global_store_dwordx4 v[216:217], v[180:183], off offset:64
	s_waitcnt vmcnt(7)
	v_lshlrev_b32_e32 v218, 16, v198
	v_and_b32_e32 v219, 0xffff0000, v198
	v_lshlrev_b32_e32 v220, 16, v199
	v_and_b32_e32 v221, 0xffff0000, v199
	v_fma_f32 v184, v4, v218, v184
	v_fma_f32 v185, v5, v219, v185
	v_fma_f32 v186, v6, v220, v186
	v_fma_f32 v187, v7, v221, v187
	global_store_dwordx4 v[216:217], v[184:187], off offset:512
	s_waitcnt vmcnt(7)
	v_lshlrev_b32_e32 v218, 16, v200
	v_and_b32_e32 v219, 0xffff0000, v200
	v_lshlrev_b32_e32 v220, 16, v201
	v_and_b32_e32 v221, 0xffff0000, v201
	v_fma_f32 v188, v0, v218, v188
	v_fma_f32 v189, v1, v219, v189
	v_fma_f32 v190, v2, v220, v190
	v_fma_f32 v191, v3, v221, v191
	global_store_dwordx4 v[216:217], v[188:191], off offset:576
	s_cbranch_vccnz .LBB0_265
	s_andn2_b64 vcc, exec, s[68:69]
	s_cbranch_vccnz .LBB0_264
	s_barrier
	s_branch .LBB0_264

; DEV bf16_t f2bf(float x) { return (bf16_t)(cvtpk(x, 0.f) & 0xffffu); }
; DEV int crow(int r, int hi) { return (r & 3) + 8 * (r >> 2) + 4 * hi; }
; #define TIDX() const int tid = ltid(), lane = tid & 63, wid = tid >> 6, r32 = lane & 31, hi = lane >> 5, wm = wid & 3, wn = wid >> 2; (void)lane; (void)wid; (void)r32; (void)hi; (void)wm; (void)wn
; DEV void run_phase(const Params& p, const int grp, const int l, const int ph, char* lds) {
;     ...
;             TIDX();
;             const float* rs_l = (const float*)(lds + GemmCfg<2>::RS_OFF);
;             const int h = n0 >> 8;
; #pragma unroll
;             for (int mi = 0; mi < 2; ++mi) {
;               const int rbl = wm * 64 + mi * 32;
; #pragma unroll
;               for (int nf = 0; nf < 4; ++nf) {
;                 const int j = nf * 32 + r32;
; #pragma unroll
;                 for (int r = 0; r < 16; ++r) {
;                   const int rl = rbl + crow(r, hi); const unsigned row = (unsigned)(m0 + rl);
;                   const bf16_t ob = f2bf(acc[mi][nf][r] * rs_l[rl]);
;                   if (wn == 0) KM[row * 1536 + h * 192 + j] = ob; else VM[row * 1024 + h * 128 + j] = ob;
;                 }
;               }
;             }
.LBB0_489:
	s_or_b64 exec, exec, s[0:1]
	s_waitcnt lgkmcnt(0)
	v_mov_b32_e32 v128, v204
	s_barrier
	v_readfirstlane_b32 s18, v204
	v_and_b32_e32 v160, 0xc0, v204
	v_lshrrev_b32_e32 v161, 3, v204
	v_and_b32_e32 v161, 4, v161
	v_or_b32_e32 v160, v160, v161
	v_lshlrev_b32_e32 v162, 2, v160
	v_add_u32_e32 v162, 0x24000, v162
	ds_read_b128 v[128:131], v162
	ds_read_b128 v[132:135], v162 offset:32
	ds_read_b128 v[136:139], v162 offset:64
	ds_read_b128 v[140:143], v162 offset:96
	ds_read_b128 v[144:147], v162 offset:128
	ds_read_b128 v[148:151], v162 offset:160
	ds_read_b128 v[152:155], v162 offset:192
	ds_read_b128 v[156:159], v162 offset:224
	s_cmpk_gt_u32 s18, 0xff
	s_cbranch_scc1 .Lkvepi_vm
	v_readlane_b32 s0, v250, 0
	v_readlane_b32 s1, v250, 1
	s_mul_i32 s19, s21, 0x180
	s_movk_i32 s26, 0xc00
	s_branch .Lkvepi_cont
.Lkvepi_vm:
	v_readlane_b32 s0, v249, 6
	v_readlane_b32 s1, v249, 7
	s_lshl_b32 s19, s21, 8
	s_movk_i32 s26, 0x800
.Lkvepi_cont:
	s_nop 3
	s_add_u32 s0, s0, s19
	s_addc_u32 s1, s1, 0
	s_mov_b32 s27, 0
	s_mul_i32 s18, s26, 5
	s_mov_b32 s19, 0
	v_add_u32_e32 v163, s3, v160
	v_and_b32_e32 v164, 31, v204
	v_lshlrev_b32_e32 v164, 1, v164
	v_mov_b32_e32 v165, 0
	v_mad_u64_u32 v[166:167], vcc, v163, s26, v[164:165]
	v_lshl_add_u64 v[166:167], s[0:1], 0, v[166:167]
	s_waitcnt lgkmcnt(0)
	v_mul_f32_e32 v160, v112, v128
	v_mul_f32_e32 v161, v96, v128
	v_mul_f32_e32 v163, v80, v128
	v_mul_f32_e32 v164, v64, v128
	v_cvt_pk_bf16_f32 v160, v160, v161
	v_cvt_pk_bf16_f32 v163, v163, v164
	global_store_short v[166:167], v160, off
	global_store_short_d16_hi v[166:167], v160, off offset:64
	global_store_short v[166:167], v163, off offset:128
	global_store_short_d16_hi v[166:167], v163, off offset:192
	v_lshl_add_u64 v[166:167], s[26:27], 0, v[166:167]
	v_mul_f32_e32 v168, v113, v129
	v_mul_f32_e32 v170, v97, v129
	v_mul_f32_e32 v171, v81, v129
	v_mul_f32_e32 v165, v65, v129
	v_cvt_pk_bf16_f32 v168, v168, v170
	v_cvt_pk_bf16_f32 v171, v171, v165
	global_store_short v[166:167], v168, off
	global_store_short_d16_hi v[166:167], v168, off offset:64
	global_store_short v[166:167], v171, off offset:128
	global_store_short_d16_hi v[166:167], v171, off offset:192
	v_lshl_add_u64 v[166:167], s[26:27], 0, v[166:167]
	v_mul_f32_e32 v160, v114, v130
	v_mul_f32_e32 v161, v98, v130
	v_mul_f32_e32 v163, v82, v130
	v_mul_f32_e32 v164, v66, v130
	v_cvt_pk_bf16_f32 v160, v160, v161
	v_cvt_pk_bf16_f32 v163, v163, v164
	global_store_short v[166:167], v160, off
	global_store_short_d16_hi v[166:167], v160, off offset:64
	global_store_short v[166:167], v163, off offset:128
	global_store_short_d16_hi v[166:167], v163, off offset:192
	v_lshl_add_u64 v[166:167], s[26:27], 0, v[166:167]
	v_mul_f32_e32 v168, v115, v131
	v_mul_f32_e32 v170, v99, v131
	v_mul_f32_e32 v171, v83, v131
	v_mul_f32_e32 v165, v67, v131
	v_cvt_pk_bf16_f32 v168, v168, v170
	v_cvt_pk_bf16_f32 v171, v171, v165
	global_store_short v[166:167], v168, off
	global_store_short_d16_hi v[166:167], v168, off offset:64
	global_store_short v[166:167], v171, off offset:128
	global_store_short_d16_hi v[166:167], v171, off offset:192
	v_lshl_add_u64 v[166:167], s[18:19], 0, v[166:167]
	v_mul_f32_e32 v160, v116, v132
	v_mul_f32_e32 v161, v100, v132
	v_mul_f32_e32 v163, v84, v132
	v_mul_f32_e32 v164, v68, v132
	v_cvt_pk_bf16_f32 v160, v160, v161
	v_cvt_pk_bf16_f32 v163, v163, v164
	global_store_short v[166:167], v160, off
	global_store_short_d16_hi v[166:167], v160, off offset:64
	global_store_short v[166:167], v163, off offset:128
	global_store_short_d16_hi v[166:167], v163, off offset:192
	v_lshl_add_u64 v[166:167], s[26:27], 0, v[166:167]
	v_mul_f32_e32 v168, v117, v133
	v_mul_f32_e32 v170, v101, v133
	v_mul_f32_e32 v171, v85, v133
	v_mul_f32_e32 v165, v69, v133
	v_cvt_pk_bf16_f32 v168, v168, v170
	v_cvt_pk_bf16_f32 v171, v171, v165
	global_store_short v[166:167], v168, off
	global_store_short_d16_hi v[166:167], v168, off offset:64
	global_store_short v[166:167], v171, off offset:128
	global_store_short_d16_hi v[166:167], v171, off offset:192
	v_lshl_add_u64 v[166:167], s[26:27], 0, v[166:167]
	v_mul_f32_e32 v160, v118, v134
	v_mul_f32_e32 v161, v102, v134
	v_mul_f32_e32 v163, v86, v134
	v_mul_f32_e32 v164, v70, v134
	v_cvt_pk_bf16_f32 v160, v160, v161
	v_cvt_pk_bf16_f32 v163, v163, v164
	global_store_short v[166:167], v160, off
	global_store_short_d16_hi v[166:167], v160, off offset:64
	global_store_short v[166:167], v163, off offset:128
	global_store_short_d16_hi v[166:167], v163, off offset:192
	v_lshl_add_u64 v[166:167], s[26:27], 0, v[166:167]
	v_mul_f32_e32 v168, v119, v135
	v_mul_f32_e32 v170, v103, v135
	v_mul_f32_e32 v171, v87, v135
	v_mul_f32_e32 v165, v71, v135
	v_cvt_pk_bf16_f32 v168, v168, v170
	v_cvt_pk_bf16_f32 v171, v171, v165
	global_store_short v[166:167], v168, off
	global_store_short_d16_hi v[166:167], v168, off offset:64
	global_store_short v[166:167], v171, off offset:128
	global_store_short_d16_hi v[166:167], v171, off offset:192
	v_lshl_add_u64 v[166:167], s[18:19], 0, v[166:167]
	v_mul_f32_e32 v160, v120, v136
	v_mul_f32_e32 v161, v104, v136
	v_mul_f32_e32 v163, v88, v136
	v_mul_f32_e32 v164, v72, v136
	v_cvt_pk_bf16_f32 v160, v160, v161
	v_cvt_pk_bf16_f32 v163, v163, v164
	global_store_short v[166:167], v160, off
	global_store_short_d16_hi v[166:167], v160, off offset:64
	global_store_short v[166:167], v163, off offset:128
	global_store_short_d16_hi v[166:167], v163, off offset:192
	v_lshl_add_u64 v[166:167], s[26:27], 0, v[166:167]
	v_mul_f32_e32 v168, v121, v137
	v_mul_f32_e32 v170, v105, v137
	v_mul_f32_e32 v171, v89, v137
	v_mul_f32_e32 v165, v73, v137
	v_cvt_pk_bf16_f32 v168, v168, v170
; DEV bf16_t f2bf(float x) { return (bf16_t)(cvtpk(x, 0.f) & 0xffffu); }
; DEV int crow(int r, int hi) { return (r & 3) + 8 * (r >> 2) + 4 * hi; }
; DEV void run_phase(const Params& p, const int grp, const int l, const int ph, char* lds) {
;     ...
; #pragma unroll
;             for (int mi = 0; mi < 2; ++mi) {
;               const int rbl = wm * 64 + mi * 32;
; #pragma unroll
;               for (int nf = 0; nf < 4; ++nf) {
;                 const int j = nf * 32 + r32;
; #pragma unroll
;                 for (int r = 0; r < 16; ++r) {
;                   const int rl = rbl + crow(r, hi); const unsigned row = (unsigned)(m0 + rl);
;                   const bf16_t ob = f2bf(acc[mi][nf][r] * rs_l[rl]);
;                   if (wn == 0) KM[row * 1536 + h * 192 + j] = ob; else VM[row * 1024 + h * 128 + j] = ob;
;                 }
;               }
;             }
	v_cvt_pk_bf16_f32 v171, v171, v165
	global_store_short v[166:167], v168, off
	global_store_short_d16_hi v[166:167], v168, off offset:64
	global_store_short v[166:167], v171, off offset:128
	global_store_short_d16_hi v[166:167], v171, off offset:192
	v_lshl_add_u64 v[166:167], s[26:27], 0, v[166:167]
	v_mul_f32_e32 v160, v122, v138
	v_mul_f32_e32 v161, v106, v138
	v_mul_f32_e32 v163, v90, v138
	v_mul_f32_e32 v164, v74, v138
	v_cvt_pk_bf16_f32 v160, v160, v161
	v_cvt_pk_bf16_f32 v163, v163, v164
	global_store_short v[166:167], v160, off
	global_store_short_d16_hi v[166:167], v160, off offset:64
	global_store_short v[166:167], v163, off offset:128
	global_store_short_d16_hi v[166:167], v163, off offset:192
	v_lshl_add_u64 v[166:167], s[26:27], 0, v[166:167]
	v_mul_f32_e32 v168, v123, v139
	v_mul_f32_e32 v170, v107, v139
	v_mul_f32_e32 v171, v91, v139
	v_mul_f32_e32 v165, v75, v139
	v_cvt_pk_bf16_f32 v168, v168, v170
	v_cvt_pk_bf16_f32 v171, v171, v165
	global_store_short v[166:167], v168, off
	global_store_short_d16_hi v[166:167], v168, off offset:64
	global_store_short v[166:167], v171, off offset:128
	global_store_short_d16_hi v[166:167], v171, off offset:192
	v_lshl_add_u64 v[166:167], s[18:19], 0, v[166:167]
	v_mul_f32_e32 v160, v124, v140
	v_mul_f32_e32 v161, v108, v140
	v_mul_f32_e32 v163, v92, v140
	v_mul_f32_e32 v164, v76, v140
	v_cvt_pk_bf16_f32 v160, v160, v161
	v_cvt_pk_bf16_f32 v163, v163, v164
	global_store_short v[166:167], v160, off
	global_store_short_d16_hi v[166:167], v160, off offset:64
	global_store_short v[166:167], v163, off offset:128
	global_store_short_d16_hi v[166:167], v163, off offset:192
	v_lshl_add_u64 v[166:167], s[26:27], 0, v[166:167]
	v_mul_f32_e32 v168, v125, v141
	v_mul_f32_e32 v170, v109, v141
	v_mul_f32_e32 v171, v93, v141
	v_mul_f32_e32 v165, v77, v141
	v_cvt_pk_bf16_f32 v168, v168, v170
	v_cvt_pk_bf16_f32 v171, v171, v165
	global_store_short v[166:167], v168, off
	global_store_short_d16_hi v[166:167], v168, off offset:64
	global_store_short v[166:167], v171, off offset:128
	global_store_short_d16_hi v[166:167], v171, off offset:192
	v_lshl_add_u64 v[166:167], s[26:27], 0, v[166:167]
	v_mul_f32_e32 v160, v126, v142
	v_mul_f32_e32 v161, v110, v142
	v_mul_f32_e32 v163, v94, v142
	v_mul_f32_e32 v164, v78, v142
	v_cvt_pk_bf16_f32 v160, v160, v161
	v_cvt_pk_bf16_f32 v163, v163, v164
	global_store_short v[166:167], v160, off
	global_store_short_d16_hi v[166:167], v160, off offset:64
	global_store_short v[166:167], v163, off offset:128
	global_store_short_d16_hi v[166:167], v163, off offset:192
	v_lshl_add_u64 v[166:167], s[26:27], 0, v[166:167]
	v_mul_f32_e32 v168, v127, v143
	v_mul_f32_e32 v170, v111, v143
	v_mul_f32_e32 v171, v95, v143
	v_mul_f32_e32 v165, v79, v143
	v_cvt_pk_bf16_f32 v168, v168, v170
	v_cvt_pk_bf16_f32 v171, v171, v165
	global_store_short v[166:167], v168, off
	global_store_short_d16_hi v[166:167], v168, off offset:64
	global_store_short v[166:167], v171, off offset:128
	global_store_short_d16_hi v[166:167], v171, off offset:192
	v_lshl_add_u64 v[166:167], s[18:19], 0, v[166:167]
	v_mul_f32_e32 v160, v48, v144
	v_mul_f32_e32 v161, v32, v144
	v_mul_f32_e32 v163, v16, v144
	v_mul_f32_e32 v164, v0, v144
	v_cvt_pk_bf16_f32 v160, v160, v161
	v_cvt_pk_bf16_f32 v163, v163, v164
	global_store_short v[166:167], v160, off
	global_store_short_d16_hi v[166:167], v160, off offset:64
	global_store_short v[166:167], v163, off offset:128
	global_store_short_d16_hi v[166:167], v163, off offset:192
	v_lshl_add_u64 v[166:167], s[26:27], 0, v[166:167]
	v_mul_f32_e32 v168, v49, v145
	v_mul_f32_e32 v170, v33, v145
	v_mul_f32_e32 v171, v17, v145
	v_mul_f32_e32 v165, v1, v145
	v_cvt_pk_bf16_f32 v168, v168, v170
	v_cvt_pk_bf16_f32 v171, v171, v165
	global_store_short v[166:167], v168, off
	global_store_short_d16_hi v[166:167], v168, off offset:64
	global_store_short v[166:167], v171, off offset:128
	global_store_short_d16_hi v[166:167], v171, off offset:192
	v_lshl_add_u64 v[166:167], s[26:27], 0, v[166:167]
	v_mul_f32_e32 v160, v50, v146
	v_mul_f32_e32 v161, v34, v146
	v_mul_f32_e32 v163, v18, v146
	v_mul_f32_e32 v164, v2, v146
	v_cvt_pk_bf16_f32 v160, v160, v161
	v_cvt_pk_bf16_f32 v163, v163, v164
	global_store_short v[166:167], v160, off
	global_store_short_d16_hi v[166:167], v160, off offset:64
	global_store_short v[166:167], v163, off offset:128
	global_store_short_d16_hi v[166:167], v163, off offset:192
	v_lshl_add_u64 v[166:167], s[26:27], 0, v[166:167]
	v_mul_f32_e32 v168, v51, v147
	v_mul_f32_e32 v170, v35, v147
	v_mul_f32_e32 v171, v19, v147
	v_mul_f32_e32 v165, v3, v147
	v_cvt_pk_bf16_f32 v168, v168, v170
	v_cvt_pk_bf16_f32 v171, v171, v165
	global_store_short v[166:167], v168, off
	global_store_short_d16_hi v[166:167], v168, off offset:64
	global_store_short v[166:167], v171, off offset:128
	global_store_short_d16_hi v[166:167], v171, off offset:192
	v_lshl_add_u64 v[166:167], s[18:19], 0, v[166:167]
	v_mul_f32_e32 v160, v52, v148
	v_mul_f32_e32 v161, v36, v148
	v_mul_f32_e32 v163, v20, v148
	v_mul_f32_e32 v164, v4, v148
	v_cvt_pk_bf16_f32 v160, v160, v161
	v_cvt_pk_bf16_f32 v163, v163, v164
	global_store_short v[166:167], v160, off
	global_store_short_d16_hi v[166:167], v160, off offset:64
; DEV bf16_t f2bf(float x) { return (bf16_t)(cvtpk(x, 0.f) & 0xffffu); }
; DEV int crow(int r, int hi) { return (r & 3) + 8 * (r >> 2) + 4 * hi; }
; DEV void run_phase(const Params& p, const int grp, const int l, const int ph, char* lds) {
;     ...
; #pragma unroll
;             for (int mi = 0; mi < 2; ++mi) {
;               const int rbl = wm * 64 + mi * 32;
; #pragma unroll
;               for (int nf = 0; nf < 4; ++nf) {
;                 const int j = nf * 32 + r32;
; #pragma unroll
;                 for (int r = 0; r < 16; ++r) {
;                   const int rl = rbl + crow(r, hi); const unsigned row = (unsigned)(m0 + rl);
;                   const bf16_t ob = f2bf(acc[mi][nf][r] * rs_l[rl]);
;                   if (wn == 0) KM[row * 1536 + h * 192 + j] = ob; else VM[row * 1024 + h * 128 + j] = ob;
;                 }
;               }
;             }
	global_store_short v[166:167], v163, off offset:128
	global_store_short_d16_hi v[166:167], v163, off offset:192
	v_lshl_add_u64 v[166:167], s[26:27], 0, v[166:167]
	v_mul_f32_e32 v168, v53, v149
	v_mul_f32_e32 v170, v37, v149
	v_mul_f32_e32 v171, v21, v149
	v_mul_f32_e32 v165, v5, v149
	v_cvt_pk_bf16_f32 v168, v168, v170
	v_cvt_pk_bf16_f32 v171, v171, v165
	global_store_short v[166:167], v168, off
	global_store_short_d16_hi v[166:167], v168, off offset:64
	global_store_short v[166:167], v171, off offset:128
	global_store_short_d16_hi v[166:167], v171, off offset:192
	v_lshl_add_u64 v[166:167], s[26:27], 0, v[166:167]
	v_mul_f32_e32 v160, v54, v150
	v_mul_f32_e32 v161, v38, v150
	v_mul_f32_e32 v163, v22, v150
	v_mul_f32_e32 v164, v6, v150
	v_cvt_pk_bf16_f32 v160, v160, v161
	v_cvt_pk_bf16_f32 v163, v163, v164
	global_store_short v[166:167], v160, off
	global_store_short_d16_hi v[166:167], v160, off offset:64
	global_store_short v[166:167], v163, off offset:128
	global_store_short_d16_hi v[166:167], v163, off offset:192
	v_lshl_add_u64 v[166:167], s[26:27], 0, v[166:167]
	v_mul_f32_e32 v168, v55, v151
	v_mul_f32_e32 v170, v39, v151
	v_mul_f32_e32 v171, v23, v151
	v_mul_f32_e32 v165, v7, v151
	v_cvt_pk_bf16_f32 v168, v168, v170
	v_cvt_pk_bf16_f32 v171, v171, v165
	global_store_short v[166:167], v168, off
	global_store_short_d16_hi v[166:167], v168, off offset:64
	global_store_short v[166:167], v171, off offset:128
	global_store_short_d16_hi v[166:167], v171, off offset:192
	v_lshl_add_u64 v[166:167], s[18:19], 0, v[166:167]
	v_mul_f32_e32 v160, v56, v152
	v_mul_f32_e32 v161, v40, v152
	v_mul_f32_e32 v163, v24, v152
	v_mul_f32_e32 v164, v8, v152
	v_cvt_pk_bf16_f32 v160, v160, v161
	v_cvt_pk_bf16_f32 v163, v163, v164
	global_store_short v[166:167], v160, off
	global_store_short_d16_hi v[166:167], v160, off offset:64
	global_store_short v[166:167], v163, off offset:128
	global_store_short_d16_hi v[166:167], v163, off offset:192
	v_lshl_add_u64 v[166:167], s[26:27], 0, v[166:167]
	v_mul_f32_e32 v168, v57, v153
	v_mul_f32_e32 v170, v41, v153
	v_mul_f32_e32 v171, v25, v153
	v_mul_f32_e32 v165, v9, v153
	v_cvt_pk_bf16_f32 v168, v168, v170
	v_cvt_pk_bf16_f32 v171, v171, v165
	global_store_short v[166:167], v168, off
	global_store_short_d16_hi v[166:167], v168, off offset:64
	global_store_short v[166:167], v171, off offset:128
	global_store_short_d16_hi v[166:167], v171, off offset:192
	v_lshl_add_u64 v[166:167], s[26:27], 0, v[166:167]
	v_mul_f32_e32 v160, v58, v154
	v_mul_f32_e32 v161, v42, v154
	v_mul_f32_e32 v163, v26, v154
	v_mul_f32_e32 v164, v10, v154
	v_cvt_pk_bf16_f32 v160, v160, v161
	v_cvt_pk_bf16_f32 v163, v163, v164
	global_store_short v[166:167], v160, off
	global_store_short_d16_hi v[166:167], v160, off offset:64
	global_store_short v[166:167], v163, off offset:128
	global_store_short_d16_hi v[166:167], v163, off offset:192
	v_lshl_add_u64 v[166:167], s[26:27], 0, v[166:167]
	v_mul_f32_e32 v168, v59, v155
	v_mul_f32_e32 v170, v43, v155
	v_mul_f32_e32 v171, v27, v155
	v_mul_f32_e32 v165, v11, v155
	v_cvt_pk_bf16_f32 v168, v168, v170
	v_cvt_pk_bf16_f32 v171, v171, v165
	global_store_short v[166:167], v168, off
	global_store_short_d16_hi v[166:167], v168, off offset:64
	global_store_short v[166:167], v171, off offset:128
	global_store_short_d16_hi v[166:167], v171, off offset:192
	v_lshl_add_u64 v[166:167], s[18:19], 0, v[166:167]
	v_mul_f32_e32 v160, v60, v156
	v_mul_f32_e32 v161, v44, v156
	v_mul_f32_e32 v163, v28, v156
	v_mul_f32_e32 v164, v12, v156
	v_cvt_pk_bf16_f32 v160, v160, v161
	v_cvt_pk_bf16_f32 v163, v163, v164
	global_store_short v[166:167], v160, off
	global_store_short_d16_hi v[166:167], v160, off offset:64
	global_store_short v[166:167], v163, off offset:128
	global_store_short_d16_hi v[166:167], v163, off offset:192
	v_lshl_add_u64 v[166:167], s[26:27], 0, v[166:167]
	v_mul_f32_e32 v168, v61, v157
	v_mul_f32_e32 v170, v45, v157
	v_mul_f32_e32 v171, v29, v157
	v_mul_f32_e32 v165, v13, v157
	v_cvt_pk_bf16_f32 v168, v168, v170
	v_cvt_pk_bf16_f32 v171, v171, v165
	global_store_short v[166:167], v168, off
	global_store_short_d16_hi v[166:167], v168, off offset:64
	global_store_short v[166:167], v171, off offset:128
	global_store_short_d16_hi v[166:167], v171, off offset:192
	v_lshl_add_u64 v[166:167], s[26:27], 0, v[166:167]
	v_mul_f32_e32 v160, v62, v158
	v_mul_f32_e32 v161, v46, v158
	v_mul_f32_e32 v163, v30, v158
	v_mul_f32_e32 v164, v14, v158
	v_cvt_pk_bf16_f32 v160, v160, v161
	v_cvt_pk_bf16_f32 v163, v163, v164
	global_store_short v[166:167], v160, off
	global_store_short_d16_hi v[166:167], v160, off offset:64
	global_store_short v[166:167], v163, off offset:128
	global_store_short_d16_hi v[166:167], v163, off offset:192
	v_lshl_add_u64 v[166:167], s[26:27], 0, v[166:167]
	v_mul_f32_e32 v168, v63, v159
	v_mul_f32_e32 v170, v47, v159
	v_mul_f32_e32 v171, v31, v159
	v_mul_f32_e32 v165, v15, v159
	v_cvt_pk_bf16_f32 v168, v168, v170
	v_cvt_pk_bf16_f32 v171, v171, v165
	global_store_short v[166:167], v168, off
	global_store_short_d16_hi v[166:167], v168, off offset:64
	global_store_short v[166:167], v171, off offset:128
	global_store_short_d16_hi v[166:167], v171, off offset:192
	s_branch .LBB0_478
